# weight conversion of later layers moved from the prologue phase into the idle tail of the RETIN GEMM phases (workgroups without a seventh unit)
# speedup vs baseline: 1.0076x; 1.0076x over previous
; #define LAS __attribute__((address_space(3)))
; __device__ __forceinline__ void ph_p0(const Params& p, LAS unsigned char* lds, int tid, int lane, int wave) {
;     unsigned char* ws = p.ws;
;     LAS float* scr = (LAS float*)(lds + wave * 16384);
;     const int gw = blockIdx.x * NWAVES + wave, NGW = gridDim.x * NWAVES;
;     constexpr int C_WIN = 2 * 16 * 192, C_WOUT = 2 * 32 * 32, C_RKV = 2 * 3 * 512, C_W1 = 2 * 32, C_A1 = 2 * 32, C_G1 = 2 * 80, C_V1 = 16, C_WO = 2 * 512, C_WUG = 4 * 16 * 176, C_WD = 4 * 44 * 32;
;     constexpr int NITEMS = C_WIN + C_WOUT + C_RKV + C_W1 + C_A1 + C_G1 + C_V1 + C_WO + C_WUG + C_WD;
;     for (int it = gw; it < NITEMS; it += NGW) {
;         int r = it;
;         if (r < C_WIN) { const int j = r / 3072, q = r % 3072, kb = q / 192, nb = q % 192;
.LBB0_1410:
	s_and_b64 vcc, exec, s[40:41]
	v_readlane_b32 s40, v254, 60
	v_readlane_b32 s30, v254, 56
	v_readlane_b32 s34, v254, 58
	v_readlane_b32 s41, v254, 61
	v_readlane_b32 s44, v255, 0
	v_readlane_b32 s45, v255, 1
	v_readlane_b32 s48, v255, 4
	v_readlane_b32 s49, v255, 5
	v_readlane_b32 s50, v255, 6
	v_readlane_b32 s51, v255, 7
	v_readlane_b32 s52, v255, 8
	v_readlane_b32 s53, v255, 9
	v_readlane_b32 s31, v254, 57
	v_readlane_b32 s35, v254, 59
	v_readlane_b32 s42, v254, 62
	v_readlane_b32 s43, v254, 63
	v_readlane_b32 s46, v255, 2
	v_readlane_b32 s47, v255, 3
	v_readlane_b32 s54, v255, 10
	v_readlane_b32 s55, v255, 11
	s_cbranch_vccz .LBB0_1548
	v_readlane_b32 s0, v255, 14
	s_and_b32 s0, 0xffff, s0
	s_cmp_lg_u32 s0, 0
	s_cbranch_scc1 .LBB0_1547
	s_load_dword s6, s[88:89], 0x0
	v_readlane_b32 s0, v253, 1
	v_readlane_b32 s1, v255, 15
	s_add_i32 s2, s1, s0
	s_waitcnt lgkmcnt(0)
	s_lshl_b32 s24, s6, 3
	s_cmp_ge_u32 s100, 4
	s_cselect_b32 s24, 0x740, s24
	s_cselect_b32 s101, 0xc0, 0
	s_sub_i32 s2, s2, s101
	s_cmpk_gt_i32 s2, 0x732f
	s_cbranch_scc1 .LBB0_1498
	s_lshl_b32 s0, s1, 14
	v_and_b32_e32 v16, 31, v194
	v_and_b32_e32 v0, 7, v194
	v_lshrrev_b32_e32 v17, 3, v238
	s_add_i32 s0, s0, 0
	v_lshlrev_b32_e32 v2, 2, v16
	v_mul_u32_u24_e32 v3, 0x420, v0
	v_lshlrev_b32_e32 v4, 2, v17
	s_waitcnt vmcnt(0)
	v_add_u32_e32 v18, s0, v2
	v_add3_u32 v19, s0, v3, v4
	v_readlane_b32 s0, v253, 8
	v_lshlrev_b32_e32 v20, 3, v0
	v_lshlrev_b32_e32 v0, 4, v0
	v_readlane_b32 s1, v253, 9
	v_readlane_b32 s8, v254, 5
	v_lshrrev_b32_e32 v14, 5, v238
	v_lshl_add_u64 v[4:5], s[0:1], 0, v[0:1]
	v_lshlrev_b32_e32 v0, 12, v17
	v_mov_b32_e32 v3, v1
	v_readlane_b32 s20, v254, 17
	v_readlane_b32 s21, v254, 18
	v_or_b32_e32 v21, 8, v17
	v_or_b32_e32 v38, 16, v17
	v_or_b32_e32 v39, 24, v17
	v_lshl_add_u64 v[22:23], v[4:5], 0, v[0:1]
	v_lshl_add_u64 v[24:25], s[20:21], 0, v[2:3]
	v_mov_b32_e32 v15, v14
	s_mov_b32 s3, s2
	v_readlane_b32 s9, v254, 6
	v_readlane_b32 s10, v254, 7
	v_readlane_b32 s11, v254, 8
	v_readlane_b32 s12, v254, 9
	v_readlane_b32 s13, v254, 10
	v_readlane_b32 s14, v254, 11
	v_readlane_b32 s15, v254, 12
	v_readlane_b32 s16, v254, 13
	v_readlane_b32 s17, v254, 14
	v_readlane_b32 s18, v254, 15
	v_readlane_b32 s19, v254, 16
	v_readlane_b32 s22, v254, 19
	v_readlane_b32 s23, v254, 20
	s_branch .LBB0_1416

; __device__ __forceinline__ void ph_p0(const Params& p, LAS unsigned char* lds, int tid, int lane, int wave) {
;     ...
;     for (int it = gw; it < NITEMS; it += NGW) {
;         int r = it;
;         if (r < C_WIN) { const int j = r / 3072, q = r % 3072, kb = q / 192, nb = q % 192;
;             tr_item(p.in[I_RWIN] + (size_t)j * D * RWIN, RWIN, 64 * kb, 32 * nb, (bf16*)(ws + WS_WIN + j * SZ_WIN), D, 32 * nb, nullptr, scr, lane, p.in[I_NMIX] + (size_t)(2 * j) * D); continue; }
;         r -= C_WIN;
;         if (r < C_WOUT) { const int j = r / 1024, q = r % 1024, kb = q / 32, nb = q % 32;
;             tr_item(p.in[I_RWOUT] + (size_t)j * RV * D, D, 64 * kb, 32 * nb, (bf16*)(ws + WS_WOUT + j * SZ_WOUT), RV, 32 * nb, nullptr, scr, lane); continue; }
;         r -= C_WOUT;
;         if (r < C_RKV) { const int j = r / 1536, q = r % 1536, s = q / 512, q2 = q % 512, kb = q2 / 32, nb = q2 % 32, c = (s == 0 ? 0 : (s == 1 ? 2 : 3));
;             tr_item(p.in[I_WRKV] + (size_t)(j * 3 + s) * D * D, D, 64 * kb, 32 * nb, (bf16*)(ws + WS_WRW + j * SZ_WRW), KRW, s * 1024 + 32 * nb, p.in[I_MU] + (size_t)(j * 6 + c) * D, scr, lane); continue; }
;         r -= C_RKV;
;         if (r < C_W1) { const int j = r / 32, q = r % 32, kb = q / 2, nb = q % 2;
;             tr_item(p.in[I_W1] + (size_t)j * D * LW, LW, 64 * kb, 32 * nb, (bf16*)(ws + WS_WRW + j * SZ_WRW), KRW, 3072 + 32 * nb, p.in[I_MU] + (size_t)(j * 6 + 1) * D, scr, lane); continue; }
;         r -= C_W1;
;         if (r < C_A1) { const int j = r / 32, q = r % 32, kb = q / 2, nb = q % 2;
;             tr_item(p.in[I_A1] + (size_t)j * D * LA, LA, 64 * kb, 32 * nb, (bf16*)(ws + WS_WRW + j * SZ_WRW), KRW, 3136 + 32 * nb, p.in[I_MU] + (size_t)(j * 6 + 4) * D, scr, lane); continue; }
;         r -= C_A1;
;         if (r < C_G1) { const int j = r / 80, q = r % 80, kb = q / 5, nb = q % 5;
;             tr_item(p.in[I_G1] + (size_t)j * D * LG, LG, 64 * kb, 32 * nb, (bf16*)(ws + WS_WRW + j * SZ_WRW), KRW, 3200 + 32 * nb, p.in[I_MU] + (size_t)(j * 6 + 5) * D, scr, lane); continue; }
;         r -= C_G1;
;         if (r < C_V1) { const int kb = r;
;             tr_item(p.in[I_V1], LV, 64 * kb, 0, (bf16*)(ws + WS_WRW + 1 * SZ_WRW), KRW, 3360, p.in[I_MU] + (size_t)(1 * 6 + 3) * D, scr, lane); continue; }
;         r -= C_V1;
;         if (r < C_WO) { const int j = r / 512, q = r % 512, kb = q / 32, nb = q % 32;
.LBB0_1416:
	s_mov_b32 s101, 2
	s_cmp_lt_u32 s3, 0x6830
	s_cselect_b32 s101, 1, s101
	s_cmp_lt_u32 s3, 0x62b0
	s_cselect_b32 s101, 0, s101
	s_cmp_lt_u32 s3, 0x5d30
	s_cselect_b32 s101, 2, s101
	s_cmp_lt_u32 s3, 0x4730
	s_cselect_b32 s101, 1, s101
	s_cmp_lt_u32 s3, 0x3c30
	s_cselect_b32 s101, 0, s101
	s_cmp_lt_u32 s3, 0x3130
	s_cselect_b32 s101, 2, s101
	s_cmp_lt_u32 s3, 0x2f30
	s_cselect_b32 s101, 1, s101
	s_cmp_lt_u32 s3, 0x2d30
	s_cselect_b32 s101, 2, s101
	s_cmp_lt_u32 s3, 0x2cd0
	s_cselect_b32 s101, 1, s101
	s_cmp_lt_u32 s3, 0x2c80
	s_cselect_b32 s101, 2, s101
	s_cmp_lt_u32 s3, 0x2c60
	s_cselect_b32 s101, 1, s101
	s_cmp_lt_u32 s3, 0x2c40
	s_cselect_b32 s101, 2, s101
	s_cmp_lt_u32 s3, 0x2c20
	s_cselect_b32 s101, 1, s101
	s_cmp_lt_u32 s3, 0x2c00
	s_cselect_b32 s101, 2, s101
	s_cmp_lt_u32 s3, 0x2600
	s_cselect_b32 s101, 1, s101
	s_cmp_lt_u32 s3, 0x1c00
	s_cselect_b32 s101, 0, s101
	s_cmp_lt_u32 s3, 0x1800
	s_cselect_b32 s101, 1, s101
	s_cmp_lt_u32 s3, 0xc00
	s_cselect_b32 s101, 0, s101
	s_sub_i32 s0, s100, 3
	s_max_i32 s0, s0, 0
	s_cmp_lg_u32 s101, s0
	s_cbranch_scc1 .LBB0_1415
	s_cmpk_gt_i32 s3, 0x17ff
	s_mov_b64 s[0:1], -1
	s_cbranch_scc0 .LBB0_1468
	s_cmpk_gt_u32 s3, 0x1fff
	s_cbranch_scc0 .LBB0_1484
	s_cmpk_gt_u32 s3, 0x2bff
	s_cbranch_scc0 .LBB0_1463
	s_cmpk_gt_u32 s3, 0x2c3f
	s_cbranch_scc0 .LBB0_1458
	s_cmpk_gt_u32 s3, 0x2c7f
	s_cbranch_scc0 .LBB0_1453
	s_cmpk_gt_u32 s3, 0x2d1f
	s_cbranch_scc0 .LBB0_1448
	s_cmpk_gt_u32 s3, 0x2d2f
	s_cbranch_scc0 .LBB0_1443
	s_cmpk_gt_u32 s3, 0x312f
	s_cbranch_scc0 .LBB0_1438
	s_cmpk_gt_u32 s3, 0x5d2f
	s_cbranch_scc0 .LBB0_1428
	s_add_i32 s0, s3, 0xa2d0
	s_and_b32 s1, s0, 0xffff
	s_mul_i32 s1, s1, 0xba2f
	s_lshr_b32 s1, s1, 26
	s_mul_i32 s4, s1, 0x580
	s_sub_i32 s0, s0, s4
	v_readlane_b32 s8, v252, 0
	s_and_b32 s0, s0, 0xffff
	s_mul_i32 s4, s1, 0xb00000
	v_readlane_b32 s14, v252, 6
	v_readlane_b32 s9, v252, 1
	v_readlane_b32 s15, v252, 7
	s_add_u32 s7, s14, s4
	s_addc_u32 s9, s15, 0
	s_lshl_b32 s4, s0, 1
	s_lshl_b32 s0, s0, 5
	s_and_b32 s0, s0, 0x3e0
	s_and_b32 s4, s4, 0xfc0
	s_lshl_b32 s8, s0, 2
	s_add_u32 s8, s7, s8
	s_addc_u32 s9, s9, 0
	v_lshlrev_b32_e32 v0, 2, v16
	s_mov_b32 s5, 1
	v_lshl_add_u64 v[2:3], s[8:9], 0, v[0:1]
	s_mov_b32 s7, s4
	s_mov_b32 s8, 0
	s_mov_b32 s9, 32
	v_readlane_b32 s10, v252, 2
	v_readlane_b32 s11, v252, 3
	v_readlane_b32 s12, v252, 4
	v_readlane_b32 s13, v252, 5

; __device__ __forceinline__ void ph_p0(const Params& p, LAS unsigned char* lds, int tid, int lane, int wave) {
;     ...
;     const size_t gt = (size_t)blockIdx.x * NTHR + tid, GT = (size_t)gridDim.x * NTHR;
;     for (size_t i = gt; i < (size_t)(224 + 192) * (KRW / 8); i += GT) {
;         const int rr = (int)(i / (KRW / 8)), c8 = (int)(i % (KRW / 8));
;         const int j = rr < 224 ? 0 : 1, row = rr < 224 ? 3360 + rr : 3392 + (rr - 224);
;         *(v4u*)((bf16*)(ws + WS_WRW + j * SZ_WRW) + (size_t)row * KRW + c8 * 8) = (v4u){0u, 0u, 0u, 0u};
;     }
.LBB0_1498:
	s_cmp_ge_u32 s100, 4
	s_cbranch_scc1 .LBB0_1547
	v_readlane_b32 s0, v253, 38
	v_ashrrev_i32_e32 v195, 31, v194
	v_readlane_b32 s1, v253, 39
	s_mov_b32 s7, s95
	s_lshl_b64 s[8:9], s[6:7], 9
	v_lshl_add_u64 v[2:3], s[0:1], 0, v[194:195]
	s_mov_b64 s[0:1], 0x1a000
	v_cmp_gt_u64_e32 vcc, s[0:1], v[2:3]
	s_and_saveexec_b64 s[0:1], vcc
	s_cbranch_execz .LBB0_1501
	v_readlane_b32 s4, v253, 55
	v_readlane_b32 s5, v253, 56
	s_mov_b64 s[10:11], 0
	v_mov_b64_e32 v[6:7], v[2:3]
	v_lshl_add_u64 v[4:5], v[194:195], 3, s[4:5]
	s_lshl_b64 s[4:5], s[6:7], 12

; #define LAS __attribute__((address_space(3)))
; __device__ __forceinline__ unsigned xb_xcc_id() { return (unsigned)__builtin_amdgcn_s_getreg((3 << 11) | 20) & 0xFu; }
; __global__ void __launch_bounds__(NTHR, 2) mega(Params p, int lo, int hi) {
;     ...
;     for (int ph = lo; ph < hi; ++ph) {
;         int lid_; asm volatile("v_mbcnt_lo_u32_b32 %0, -1, 0\n\tv_mbcnt_hi_u32_b32 %0, -1, %0" : "=v"(lid_));
;         int tid = wave0 * 64 + lid_; asm volatile("" : "+v"(tid));
;         const int lane = tid & 63, wave = __builtin_amdgcn_readfirstlane(tid >> 6);
;         unsigned char* ws = p.ws;
;         const Ph P = phase_at(ph);
;         const int li = P.layer, jl = li >> 1;
;     ...
;         if (ph + 1 < hi) { XcdBarrier bar; bar.tid0 = tid == 0; bar.bar = (unsigned*)(p.ws + WS_CTL); bar.x = xb_xcc_id(); bar.st = (volatile LAS unsigned*)(lds + LDS_BYTES - 16); xcd_barrier(bar); }
;     }
.Lsub_not1:
	s_cmp_ge_u32 s100, 4
	s_cbranch_scc1 .Lp0b_ret
	s_cmp_eq_u32 s100, 0
	s_cbranch_scc0 .Lsub_fin
	s_cmp_eq_u32 s56, 1
	s_cselect_b32 s101, 4, 0
	s_cmp_eq_u32 s56, 16
	s_cselect_b32 s101, 5, s101
	s_cmp_eq_u32 s101, 0
	s_cbranch_scc1 .Lsub_fin
	v_readlane_b32 s0, v254, 37
	s_cmp_lt_u32 s0, 24
	s_cbranch_scc1 .Lsub_fin
	v_writelane_b32 v255, s56, 62
	s_mov_b32 s100, s101
	s_mov_b32 s56, 0
	s_branch .Lsub_tramp1
.Lp0b_ret:
	v_readlane_b32 s56, v255, 62
